# gla_b chunk loads prefetched one iteration ahead into a second register bank, counted wait vmcnt(8)
# baseline (speedup 1.0000x reference)
; __device__ __forceinline__ int otid() { int t = threadIdx.x; asm volatile("" : "+v"(t)); return t; }
; __device__ __forceinline__ int obid() { int t = blockIdx.x; asm volatile("" : "+s"(t)); return t; }
; __device__ __forceinline__ unsigned pack2(float lo, float hi) { const f32x2_t v = {lo, hi}; const bf16x2_t b = __builtin_convertvector(v, bf16x2_t); return __builtin_bit_cast(unsigned, b); }
; __device__ __forceinline__ float bflo(unsigned w) { return __uint_as_float(w << 16); }
; __device__ __forceinline__ float bfhi(unsigned w) { return __uint_as_float(w & 0xffff0000u); }
; __device__ void phase_gla_b(CP P) {
;     ...
;     for (int idx = obid() * NTHR + otid(); idx < 64 * 1024; idx += gridDim.x * NTHR) {
;         const int bhd = idx >> 10, e = (idx & 1023) * 8, d = e >> 7, dir = bhd & 1;
;         f32x4 S0 = (f32x4){0.f, 0.f, 0.f, 0.f}, S1 = S0;
;         bf16_t* base = GST + ((size_t)bhd * 128) * 8192 + e; const float* dbase = GDEC + ((size_t)bhd * 128) * 64 + d;
; #pragma unroll 1
;         for (int c0 = 0; c0 < 128; c0 += 8) { uint4 t[8]; float dc[8];
; #pragma unroll
;             for (int k = 0; k < 8; ++k) { const int c = dir == 0 ? c0 + k : 127 - (c0 + k); t[k] = *(const uint4*)(base + (size_t)c * 8192); dc[k] = dbase[(size_t)c * 64]; }
; #pragma unroll
;             for (int k = 0; k < 8; ++k) { const int c = dir == 0 ? c0 + k : 127 - (c0 + k);
;                 uint4 o; o.x = pack2(S0[0], S0[1]); o.y = pack2(S0[2], S0[3]); o.z = pack2(S1[0], S1[1]); o.w = pack2(S1[2], S1[3]); *(uint4*)(base + (size_t)c * 8192) = o;
;                 S0 = dc[k] * S0 + (f32x4){bflo(t[k].x), bfhi(t[k].x), bflo(t[k].y), bfhi(t[k].y)}; S1 = dc[k] * S1 + (f32x4){bflo(t[k].z), bfhi(t[k].z), bflo(t[k].w), bfhi(t[k].w)}; } }
.LBB0_162:
	v_ashrrev_i32_e32 v0, 10, v45
	v_ashrrev_i32_e32 v1, 31, v0
	v_lshlrev_b64 v[2:3], 21, v[0:1]
	v_lshlrev_b32_e32 v4, 4, v45
	v_lshl_add_u64 v[2:3], s[44:45], 0, v[2:3]
	v_and_b32_e32 v4, 0x3ff0, v4
	v_mov_b32_e32 v5, v184
	v_lshl_add_u64 v[32:33], v[2:3], 0, v[4:5]
	v_lshlrev_b64 v[0:1], 15, v[0:1]
	v_lshrrev_b32_e32 v2, 2, v45
	v_lshl_add_u64 v[0:1], s[30:31], 0, v[0:1]
	v_and_b32_e32 v2, 0xfc, v2
	v_mov_b32_e32 v3, v184
	v_lshl_add_u64 v[34:35], v[0:1], 0, v[2:3]
	v_and_b32_e32 v0, 0x400, v45
	v_mov_b32_e32 v36, 0
	s_mov_b32 s11, 0
	v_cmp_eq_u32_e32 vcc, 0, v0
	s_movk_i32 s12, 0x78
	v_mov_b32_e32 v37, v36
	v_mov_b32_e32 v38, v36
	v_mov_b32_e32 v39, v36
	v_mov_b32_e32 v40, v36
	v_mov_b32_e32 v41, v36
	v_mov_b32_e32 v42, v36
	v_mov_b32_e32 v43, v36
	v_mov_b32_e32 v144, 0xffffc000
	v_mov_b32_e32 v148, 0x4000
	v_mov_b32_e32 v146, 0xffffff00
	v_mov_b32_e32 v149, 0x100
	v_cndmask_b32_e32 v144, v144, v148, vcc
	v_cndmask_b32_e32 v146, v146, v149, vcc
	v_ashrrev_i32_e32 v145, 31, v144
	v_ashrrev_i32_e32 v147, 31, v146
	v_mov_b32_e32 v140, 0x7f
	v_mov_b32_e32 v141, 0
	v_cndmask_b32_e32 v142, v140, v141, vcc
	v_lshlrev_b32_e32 v150, 14, v142
	v_mov_b32_e32 v151, 0
	v_lshlrev_b32_e32 v152, 8, v142
	v_mov_b32_e32 v153, 0
	v_lshl_add_u64 v[150:151], v[32:33], 0, v[150:151]
	v_lshl_add_u64 v[152:153], v[34:35], 0, v[152:153]
	global_load_dwordx4 v[100:103], v[150:151], off
	global_load_dword v132, v[152:153], off
	v_lshl_add_u64 v[150:151], v[150:151], 0, v[144:145]
	v_lshl_add_u64 v[152:153], v[152:153], 0, v[146:147]
	global_load_dwordx4 v[104:107], v[150:151], off
	global_load_dword v133, v[152:153], off
	v_lshl_add_u64 v[150:151], v[150:151], 0, v[144:145]
	v_lshl_add_u64 v[152:153], v[152:153], 0, v[146:147]
	global_load_dwordx4 v[108:111], v[150:151], off
	global_load_dword v134, v[152:153], off
	v_lshl_add_u64 v[150:151], v[150:151], 0, v[144:145]
	v_lshl_add_u64 v[152:153], v[152:153], 0, v[146:147]
	global_load_dwordx4 v[112:115], v[150:151], off
	global_load_dword v135, v[152:153], off
	v_lshl_add_u64 v[150:151], v[150:151], 0, v[144:145]
	v_lshl_add_u64 v[152:153], v[152:153], 0, v[146:147]
	global_load_dwordx4 v[116:119], v[150:151], off
	global_load_dword v136, v[152:153], off
	v_lshl_add_u64 v[150:151], v[150:151], 0, v[144:145]
	v_lshl_add_u64 v[152:153], v[152:153], 0, v[146:147]
	global_load_dwordx4 v[120:123], v[150:151], off
	global_load_dword v137, v[152:153], off
	v_lshl_add_u64 v[150:151], v[150:151], 0, v[144:145]
	v_lshl_add_u64 v[152:153], v[152:153], 0, v[146:147]
	global_load_dwordx4 v[124:127], v[150:151], off
	global_load_dword v138, v[152:153], off
	v_lshl_add_u64 v[150:151], v[150:151], 0, v[144:145]
	v_lshl_add_u64 v[152:153], v[152:153], 0, v[146:147]
	global_load_dwordx4 v[128:131], v[150:151], off
	global_load_dword v139, v[152:153], off
	s_waitcnt vmcnt(0)
.LBB0_163:
	s_add_i32 s13, s12, 7
	v_mov_b32_e32 v0, s13
	v_mov_b32_e32 v1, s11
	v_cndmask_b32_e32 v72, v0, v1, vcc
	v_mov_b32_e32 v73, v184
	v_lshlrev_b64 v[0:1], 14, v[72:73]
	v_lshl_add_u64 v[0:1], v[32:33], 0, v[0:1]
	v_lshlrev_b64 v[0:1], 8, v[72:73]
	v_lshl_add_u64 v[0:1], v[34:35], 0, v[0:1]
	s_add_i32 s13, s12, 6
	s_add_i32 s16, s11, 1
	v_mov_b32_e32 v0, s13
	v_mov_b32_e32 v1, s16
	v_cndmask_b32_e32 v74, v0, v1, vcc
	v_mov_b32_e32 v75, v184
	v_lshlrev_b64 v[0:1], 14, v[74:75]
	v_lshl_add_u64 v[0:1], v[32:33], 0, v[0:1]
	v_lshlrev_b64 v[0:1], 8, v[74:75]
	v_lshl_add_u64 v[0:1], v[34:35], 0, v[0:1]
	s_add_i32 s13, s12, 5
	s_add_i32 s16, s11, 2
	v_mov_b32_e32 v0, s13
	v_mov_b32_e32 v1, s16
	v_cndmask_b32_e32 v68, v0, v1, vcc
	v_mov_b32_e32 v69, v184
	v_lshlrev_b64 v[0:1], 14, v[68:69]
	v_lshl_add_u64 v[0:1], v[32:33], 0, v[0:1]
	v_lshlrev_b64 v[0:1], 8, v[68:69]
	v_lshl_add_u64 v[0:1], v[34:35], 0, v[0:1]
	s_add_i32 s13, s12, 4
	s_add_i32 s16, s11, 3
	v_mov_b32_e32 v0, s13
	v_mov_b32_e32 v1, s16
	v_cndmask_b32_e32 v64, v0, v1, vcc
	v_mov_b32_e32 v65, v184
	v_lshlrev_b64 v[0:1], 14, v[64:65]
	v_lshl_add_u64 v[0:1], v[32:33], 0, v[0:1]
	v_lshlrev_b64 v[0:1], 8, v[64:65]
	v_lshl_add_u64 v[0:1], v[34:35], 0, v[0:1]
	s_add_i32 s13, s12, 3
	s_add_i32 s16, s11, 4
	v_mov_b32_e32 v0, s13
	v_mov_b32_e32 v1, s16
	v_cndmask_b32_e32 v60, v0, v1, vcc
	v_mov_b32_e32 v61, v184
	v_lshlrev_b64 v[0:1], 14, v[60:61]
	v_lshl_add_u64 v[0:1], v[32:33], 0, v[0:1]
	v_lshlrev_b64 v[0:1], 8, v[60:61]
	v_lshl_add_u64 v[0:1], v[34:35], 0, v[0:1]
	s_add_i32 s13, s12, 2
	s_add_i32 s16, s11, 5
	v_mov_b32_e32 v0, s13
	v_mov_b32_e32 v1, s16
	v_cndmask_b32_e32 v56, v0, v1, vcc
	v_mov_b32_e32 v57, v184
	v_lshlrev_b64 v[0:1], 14, v[56:57]
	v_lshl_add_u64 v[0:1], v[32:33], 0, v[0:1]
	v_lshlrev_b64 v[0:1], 8, v[56:57]
	v_lshl_add_u64 v[0:1], v[34:35], 0, v[0:1]
	s_add_i32 s13, s12, 1
	s_add_i32 s16, s11, 6
	v_mov_b32_e32 v0, s13
	v_mov_b32_e32 v1, s16
	v_cndmask_b32_e32 v52, v0, v1, vcc
	v_mov_b32_e32 v53, v184
	v_lshlrev_b64 v[0:1], 14, v[52:53]
	v_lshl_add_u64 v[0:1], v[32:33], 0, v[0:1]
	v_lshlrev_b64 v[0:1], 8, v[52:53]
	v_lshl_add_u64 v[0:1], v[34:35], 0, v[0:1]
	s_add_i32 s13, s11, 7
	v_mov_b32_e32 v0, s12
	v_mov_b32_e32 v1, s13
	v_cndmask_b32_e32 v48, v0, v1, vcc
	v_mov_b32_e32 v49, v184
	v_lshlrev_b64 v[0:1], 14, v[48:49]
	v_lshl_add_u64 v[0:1], v[32:33], 0, v[0:1]
	v_lshlrev_b64 v[76:77], 8, v[48:49]
	v_lshl_add_u64 v[76:77], v[34:35], 0, v[76:77]
	v_lshlrev_b32_e32 v72, 14, v72
	v_cvt_pk_bf16_f32 v76, v36, v37
	v_cvt_pk_bf16_f32 v77, v38, v39
	v_cvt_pk_bf16_f32 v78, v40, v41
	v_cvt_pk_bf16_f32 v79, v42, v43
	v_lshl_add_u64 v[72:73], v[32:33], 0, v[72:73]
	global_store_dwordx4 v[72:73], v[76:79], off
	s_waitcnt vmcnt(8)
; __device__ __forceinline__ unsigned pack2(float lo, float hi) { const f32x2_t v = {lo, hi}; const bf16x2_t b = __builtin_convertvector(v, bf16x2_t); return __builtin_bit_cast(unsigned, b); }
; __device__ __forceinline__ float bflo(unsigned w) { return __uint_as_float(w << 16); }
; __device__ __forceinline__ float bfhi(unsigned w) { return __uint_as_float(w & 0xffff0000u); }
; __device__ void phase_gla_b(CP P) {
;     ...
;         bf16_t* base = GST + ((size_t)bhd * 128) * 8192 + e; const float* dbase = GDEC + ((size_t)bhd * 128) * 64 + d;
; #pragma unroll 1
;         for (int c0 = 0; c0 < 128; c0 += 8) { uint4 t[8]; float dc[8];
; #pragma unroll
;             for (int k = 0; k < 8; ++k) { const int c = dir == 0 ? c0 + k : 127 - (c0 + k); t[k] = *(const uint4*)(base + (size_t)c * 8192); dc[k] = dbase[(size_t)c * 64]; }
; #pragma unroll
;             for (int k = 0; k < 8; ++k) { const int c = dir == 0 ? c0 + k : 127 - (c0 + k);
;                 uint4 o; o.x = pack2(S0[0], S0[1]); o.y = pack2(S0[2], S0[3]); o.z = pack2(S1[0], S1[1]); o.w = pack2(S1[2], S1[3]); *(uint4*)(base + (size_t)c * 8192) = o;
;                 S0 = dc[k] * S0 + (f32x4){bflo(t[k].x), bfhi(t[k].x), bflo(t[k].y), bfhi(t[k].y)}; S1 = dc[k] * S1 + (f32x4){bflo(t[k].z), bfhi(t[k].z), bflo(t[k].w), bfhi(t[k].w)}; } }
	v_mov_b64_e32 v[28:29], v[100:101]
	v_mov_b64_e32 v[30:31], v[102:103]
	v_mov_b32_e32 v70, v132
	v_mov_b64_e32 v[24:25], v[104:105]
	v_mov_b64_e32 v[26:27], v[106:107]
	v_mov_b32_e32 v66, v133
	v_mov_b64_e32 v[20:21], v[108:109]
	v_mov_b64_e32 v[22:23], v[110:111]
	v_mov_b32_e32 v62, v134
	v_mov_b64_e32 v[16:17], v[112:113]
	v_mov_b64_e32 v[18:19], v[114:115]
	v_mov_b32_e32 v58, v135
	v_mov_b64_e32 v[12:13], v[116:117]
	v_mov_b64_e32 v[14:15], v[118:119]
	v_mov_b32_e32 v54, v136
	v_mov_b64_e32 v[8:9], v[120:121]
	v_mov_b64_e32 v[10:11], v[122:123]
	v_mov_b32_e32 v50, v137
	v_mov_b64_e32 v[4:5], v[124:125]
	v_mov_b64_e32 v[6:7], v[126:127]
	v_mov_b32_e32 v46, v138
	v_mov_b64_e32 v[0:1], v[128:129]
	v_mov_b64_e32 v[2:3], v[130:131]
	v_mov_b32_e32 v44, v139
	s_add_i32 s13, s11, 8
	s_min_i32 s13, s13, 0x78
	s_add_i32 s16, s12, -8
	s_max_i32 s16, s16, 0
	s_add_i32 s16, s16, 7
	v_mov_b32_e32 v140, s16
	v_mov_b32_e32 v141, s13
	v_cndmask_b32_e32 v142, v140, v141, vcc
	v_lshlrev_b32_e32 v150, 14, v142
	v_mov_b32_e32 v151, 0
	v_lshlrev_b32_e32 v152, 8, v142
	v_mov_b32_e32 v153, 0
	v_lshl_add_u64 v[150:151], v[32:33], 0, v[150:151]
	v_lshl_add_u64 v[152:153], v[34:35], 0, v[152:153]
	global_load_dwordx4 v[100:103], v[150:151], off
	global_load_dword v132, v[152:153], off
	v_lshl_add_u64 v[150:151], v[150:151], 0, v[144:145]
	v_lshl_add_u64 v[152:153], v[152:153], 0, v[146:147]
	global_load_dwordx4 v[104:107], v[150:151], off
	global_load_dword v133, v[152:153], off
	v_lshl_add_u64 v[150:151], v[150:151], 0, v[144:145]
	v_lshl_add_u64 v[152:153], v[152:153], 0, v[146:147]
	global_load_dwordx4 v[108:111], v[150:151], off
	global_load_dword v134, v[152:153], off
	v_lshl_add_u64 v[150:151], v[150:151], 0, v[144:145]
	v_lshl_add_u64 v[152:153], v[152:153], 0, v[146:147]
	global_load_dwordx4 v[112:115], v[150:151], off
	global_load_dword v135, v[152:153], off
	v_lshl_add_u64 v[150:151], v[150:151], 0, v[144:145]
	v_lshl_add_u64 v[152:153], v[152:153], 0, v[146:147]
	global_load_dwordx4 v[116:119], v[150:151], off
	global_load_dword v136, v[152:153], off
	v_lshl_add_u64 v[150:151], v[150:151], 0, v[144:145]
	v_lshl_add_u64 v[152:153], v[152:153], 0, v[146:147]
	global_load_dwordx4 v[120:123], v[150:151], off
	global_load_dword v137, v[152:153], off
	v_lshl_add_u64 v[150:151], v[150:151], 0, v[144:145]
	v_lshl_add_u64 v[152:153], v[152:153], 0, v[146:147]
	global_load_dwordx4 v[124:127], v[150:151], off
	global_load_dword v138, v[152:153], off
	v_lshl_add_u64 v[150:151], v[150:151], 0, v[144:145]
	v_lshl_add_u64 v[152:153], v[152:153], 0, v[146:147]
	global_load_dwordx4 v[128:131], v[150:151], off
	global_load_dword v139, v[152:153], off
	v_lshlrev_b32_e32 v72, 16, v28
	v_and_b32_e32 v73, 0xffff0000, v28
	v_lshlrev_b32_e32 v28, 16, v29
	v_and_b32_e32 v29, 0xffff0000, v29
	s_nop 0
	v_pk_fma_f32 v[38:39], v[38:39], v[70:71], v[28:29] op_sel_hi:[1,0,1]
	v_lshlrev_b32_e32 v28, 16, v30
	v_and_b32_e32 v29, 0xffff0000, v30
	v_lshlrev_b32_e32 v30, 16, v31
	v_and_b32_e32 v31, 0xffff0000, v31
	v_pk_fma_f32 v[36:37], v[36:37], v[70:71], v[72:73] op_sel_hi:[1,0,1]
	v_pk_fma_f32 v[42:43], v[42:43], v[70:71], v[30:31] op_sel_hi:[1,0,1]
	v_pk_fma_f32 v[40:41], v[40:41], v[70:71], v[28:29] op_sel_hi:[1,0,1]
	v_lshlrev_b32_e32 v70, 14, v74
	v_mov_b32_e32 v71, v184
	v_cvt_pk_bf16_f32 v28, v36, v37
	v_cvt_pk_bf16_f32 v29, v38, v39
	v_cvt_pk_bf16_f32 v30, v40, v41
	v_cvt_pk_bf16_f32 v31, v42, v43
	v_lshl_add_u64 v[70:71], v[32:33], 0, v[70:71]
	global_store_dwordx4 v[70:71], v[28:31], off
	s_add_i32 s12, s12, -8
	s_add_i32 s13, s11, 8
	s_nop 0
	v_lshlrev_b32_e32 v28, 16, v24
	v_and_b32_e32 v29, 0xffff0000, v24
	v_lshlrev_b32_e32 v24, 16, v25
	v_and_b32_e32 v25, 0xffff0000, v25
	s_nop 0
	v_pk_fma_f32 v[30:31], v[38:39], v[66:67], v[24:25] op_sel_hi:[1,0,1]
	v_lshlrev_b32_e32 v24, 16, v26
	v_and_b32_e32 v25, 0xffff0000, v26
	v_lshlrev_b32_e32 v26, 16, v27
	v_and_b32_e32 v27, 0xffff0000, v27
	v_pk_fma_f32 v[28:29], v[36:37], v[66:67], v[28:29] op_sel_hi:[1,0,1]
	v_pk_fma_f32 v[36:37], v[42:43], v[66:67], v[26:27] op_sel_hi:[1,0,1]
	v_pk_fma_f32 v[38:39], v[40:41], v[66:67], v[24:25] op_sel_hi:[1,0,1]
	v_lshlrev_b32_e32 v40, 14, v68
	v_mov_b32_e32 v41, v184
	v_cvt_pk_bf16_f32 v24, v28, v29
	v_cvt_pk_bf16_f32 v25, v30, v31
	v_cvt_pk_bf16_f32 v26, v38, v39
	v_cvt_pk_bf16_f32 v27, v36, v37
	v_lshl_add_u64 v[40:41], v[32:33], 0, v[40:41]
	global_store_dwordx4 v[40:41], v[24:27], off
	s_cmpk_gt_u32 s11, 0x77
	s_mov_b32 s11, s13
	s_nop 0
	v_lshlrev_b32_e32 v24, 16, v20
	v_and_b32_e32 v25, 0xffff0000, v20
	v_lshlrev_b32_e32 v20, 16, v21
	v_and_b32_e32 v21, 0xffff0000, v21
	s_nop 0
	v_pk_fma_f32 v[26:27], v[30:31], v[62:63], v[20:21] op_sel_hi:[1,0,1]
	v_lshlrev_b32_e32 v20, 16, v22
; __device__ __forceinline__ unsigned pack2(float lo, float hi) { const f32x2_t v = {lo, hi}; const bf16x2_t b = __builtin_convertvector(v, bf16x2_t); return __builtin_bit_cast(unsigned, b); }
; __device__ __forceinline__ float bflo(unsigned w) { return __uint_as_float(w << 16); }
; __device__ __forceinline__ float bfhi(unsigned w) { return __uint_as_float(w & 0xffff0000u); }
; __device__ void phase_gla_b(CP P) {
;     ...
;         bf16_t* base = GST + ((size_t)bhd * 128) * 8192 + e; const float* dbase = GDEC + ((size_t)bhd * 128) * 64 + d;
; #pragma unroll 1
;         for (int c0 = 0; c0 < 128; c0 += 8) { uint4 t[8]; float dc[8];
; #pragma unroll
;             for (int k = 0; k < 8; ++k) { const int c = dir == 0 ? c0 + k : 127 - (c0 + k); t[k] = *(const uint4*)(base + (size_t)c * 8192); dc[k] = dbase[(size_t)c * 64]; }
; #pragma unroll
;             for (int k = 0; k < 8; ++k) { const int c = dir == 0 ? c0 + k : 127 - (c0 + k);
;                 uint4 o; o.x = pack2(S0[0], S0[1]); o.y = pack2(S0[2], S0[3]); o.z = pack2(S1[0], S1[1]); o.w = pack2(S1[2], S1[3]); *(uint4*)(base + (size_t)c * 8192) = o;
;                 S0 = dc[k] * S0 + (f32x4){bflo(t[k].x), bfhi(t[k].x), bflo(t[k].y), bfhi(t[k].y)}; S1 = dc[k] * S1 + (f32x4){bflo(t[k].z), bfhi(t[k].z), bflo(t[k].w), bfhi(t[k].w)}; } }
	v_and_b32_e32 v21, 0xffff0000, v22
	v_lshlrev_b32_e32 v22, 16, v23
	v_and_b32_e32 v23, 0xffff0000, v23
	v_pk_fma_f32 v[24:25], v[28:29], v[62:63], v[24:25] op_sel_hi:[1,0,1]
	v_pk_fma_f32 v[28:29], v[36:37], v[62:63], v[22:23] op_sel_hi:[1,0,1]
	v_pk_fma_f32 v[30:31], v[38:39], v[62:63], v[20:21] op_sel_hi:[1,0,1]
	v_lshlrev_b32_e32 v36, 14, v64
	v_mov_b32_e32 v37, v184
	v_cvt_pk_bf16_f32 v20, v24, v25
	v_cvt_pk_bf16_f32 v21, v26, v27
	v_cvt_pk_bf16_f32 v22, v30, v31
	v_cvt_pk_bf16_f32 v23, v28, v29
	v_lshl_add_u64 v[36:37], v[32:33], 0, v[36:37]
	global_store_dwordx4 v[36:37], v[20:23], off
	s_nop 0
	s_nop 0
	v_lshlrev_b32_e32 v20, 16, v16
	v_and_b32_e32 v21, 0xffff0000, v16
	v_lshlrev_b32_e32 v16, 16, v17
	v_and_b32_e32 v17, 0xffff0000, v17
	s_nop 0
	v_pk_fma_f32 v[22:23], v[26:27], v[58:59], v[16:17] op_sel_hi:[1,0,1]
	v_lshlrev_b32_e32 v16, 16, v18
	v_and_b32_e32 v17, 0xffff0000, v18
	v_lshlrev_b32_e32 v18, 16, v19
	v_and_b32_e32 v19, 0xffff0000, v19
	v_pk_fma_f32 v[20:21], v[24:25], v[58:59], v[20:21] op_sel_hi:[1,0,1]
	v_pk_fma_f32 v[24:25], v[28:29], v[58:59], v[18:19] op_sel_hi:[1,0,1]
	v_pk_fma_f32 v[26:27], v[30:31], v[58:59], v[16:17] op_sel_hi:[1,0,1]
	v_lshlrev_b32_e32 v28, 14, v60
	v_mov_b32_e32 v29, v184
	v_cvt_pk_bf16_f32 v16, v20, v21
	v_cvt_pk_bf16_f32 v17, v22, v23
	v_cvt_pk_bf16_f32 v18, v26, v27
	v_cvt_pk_bf16_f32 v19, v24, v25
	v_lshl_add_u64 v[28:29], v[32:33], 0, v[28:29]
	global_store_dwordx4 v[28:29], v[16:19], off
	s_nop 0
	s_nop 0
	v_lshlrev_b32_e32 v16, 16, v12
	v_and_b32_e32 v17, 0xffff0000, v12
	v_lshlrev_b32_e32 v12, 16, v13
	v_and_b32_e32 v13, 0xffff0000, v13
	s_nop 0
	v_pk_fma_f32 v[18:19], v[22:23], v[54:55], v[12:13] op_sel_hi:[1,0,1]
	v_lshlrev_b32_e32 v12, 16, v14
	v_and_b32_e32 v13, 0xffff0000, v14
	v_lshlrev_b32_e32 v14, 16, v15
	v_and_b32_e32 v15, 0xffff0000, v15
	v_pk_fma_f32 v[16:17], v[20:21], v[54:55], v[16:17] op_sel_hi:[1,0,1]
	v_pk_fma_f32 v[20:21], v[24:25], v[54:55], v[14:15] op_sel_hi:[1,0,1]
	v_pk_fma_f32 v[22:23], v[26:27], v[54:55], v[12:13] op_sel_hi:[1,0,1]
	v_lshlrev_b32_e32 v24, 14, v56
	v_mov_b32_e32 v25, v184
	v_cvt_pk_bf16_f32 v12, v16, v17
	v_cvt_pk_bf16_f32 v13, v18, v19
	v_cvt_pk_bf16_f32 v14, v22, v23
	v_cvt_pk_bf16_f32 v15, v20, v21
	v_lshl_add_u64 v[24:25], v[32:33], 0, v[24:25]
	global_store_dwordx4 v[24:25], v[12:15], off
	s_nop 0
	s_nop 0
	v_lshlrev_b32_e32 v12, 16, v8
	v_and_b32_e32 v13, 0xffff0000, v8
	v_lshlrev_b32_e32 v8, 16, v9
	v_and_b32_e32 v9, 0xffff0000, v9
	s_nop 0
	v_pk_fma_f32 v[14:15], v[18:19], v[50:51], v[8:9] op_sel_hi:[1,0,1]
	v_lshlrev_b32_e32 v8, 16, v10
	v_and_b32_e32 v9, 0xffff0000, v10
	v_lshlrev_b32_e32 v10, 16, v11
	v_and_b32_e32 v11, 0xffff0000, v11
	v_pk_fma_f32 v[12:13], v[16:17], v[50:51], v[12:13] op_sel_hi:[1,0,1]
	v_pk_fma_f32 v[16:17], v[20:21], v[50:51], v[10:11] op_sel_hi:[1,0,1]
	v_pk_fma_f32 v[18:19], v[22:23], v[50:51], v[8:9] op_sel_hi:[1,0,1]
	v_lshlrev_b32_e32 v20, 14, v52
	v_mov_b32_e32 v21, v184
	v_cvt_pk_bf16_f32 v8, v12, v13
	v_cvt_pk_bf16_f32 v9, v14, v15
	v_cvt_pk_bf16_f32 v10, v18, v19
	v_cvt_pk_bf16_f32 v11, v16, v17
	v_lshl_add_u64 v[20:21], v[32:33], 0, v[20:21]
	global_store_dwordx4 v[20:21], v[8:11], off
	s_nop 0
	s_nop 0
	v_lshlrev_b32_e32 v8, 16, v4
	v_and_b32_e32 v9, 0xffff0000, v4
	v_lshlrev_b32_e32 v4, 16, v5
	v_and_b32_e32 v5, 0xffff0000, v5
	s_nop 0
	v_pk_fma_f32 v[10:11], v[14:15], v[46:47], v[4:5] op_sel_hi:[1,0,1]
	v_lshlrev_b32_e32 v4, 16, v6
	v_and_b32_e32 v5, 0xffff0000, v6
	v_lshlrev_b32_e32 v6, 16, v7
	v_and_b32_e32 v7, 0xffff0000, v7
	v_pk_fma_f32 v[8:9], v[12:13], v[46:47], v[8:9] op_sel_hi:[1,0,1]
	v_pk_fma_f32 v[12:13], v[16:17], v[46:47], v[6:7] op_sel_hi:[1,0,1]
	v_pk_fma_f32 v[14:15], v[18:19], v[46:47], v[4:5] op_sel_hi:[1,0,1]
	v_lshlrev_b32_e32 v16, 14, v48
	v_mov_b32_e32 v17, v184
	v_cvt_pk_bf16_f32 v4, v8, v9
	v_cvt_pk_bf16_f32 v5, v10, v11
	v_cvt_pk_bf16_f32 v6, v14, v15
	v_cvt_pk_bf16_f32 v7, v12, v13
	v_lshl_add_u64 v[16:17], v[32:33], 0, v[16:17]
	global_store_dwordx4 v[16:17], v[4:7], off
	s_nop 0
	s_nop 0
	v_lshlrev_b32_e32 v4, 16, v0
	v_and_b32_e32 v5, 0xffff0000, v0
	v_lshlrev_b32_e32 v0, 16, v1
	v_and_b32_e32 v1, 0xffff0000, v1
	s_nop 0
	v_pk_fma_f32 v[38:39], v[10:11], v[44:45], v[0:1] op_sel_hi:[1,0,1]
	v_lshlrev_b32_e32 v0, 16, v2
	v_and_b32_e32 v1, 0xffff0000, v2
	v_lshlrev_b32_e32 v2, 16, v3
	v_and_b32_e32 v3, 0xffff0000, v3
	v_pk_fma_f32 v[36:37], v[8:9], v[44:45], v[4:5] op_sel_hi:[1,0,1]
	v_pk_fma_f32 v[42:43], v[12:13], v[44:45], v[2:3] op_sel_hi:[1,0,1]
	v_pk_fma_f32 v[40:41], v[14:15], v[44:45], v[0:1] op_sel_hi:[1,0,1]
	s_cbranch_scc0 .LBB0_163
	v_add_u32_e32 v45, s10, v45
	v_cmp_lt_i32_e32 vcc, s55, v45
	s_or_b64 s[38:39], vcc, s[38:39]
	s_andn2_b64 exec, exec, s[38:39]
	s_cbranch_execnz .LBB0_162
